# attention QK^T second key tile: K fragments rotated through the three spare 128-bit registers with reads three fragments ahead and counted lgkmcnt waits (same scheme as the first tile)
# speedup vs baseline: 1.0118x; 1.0054x over previous
; #define MFMA16(a, b, c) __builtin_amdgcn_mfma_f32_16x16x32_bf16((a), (b), (c), 0, 0, 0)
; __device__ __forceinline__ void attn_unit(const WS& ws, int u, bool dry = false) {
;     ...
;       const float mnew = mrun[nt];
;       float ps = 0.f;
; #pragma unroll
;       for (int mt = 0; mt < 4; ++mt)
; #pragma unroll
;         for (int jj = 0; jj < 4; ++jj) { const float pv = __builtin_amdgcn_exp2f(s[mt][nt][jj] - mnew); s[mt][nt][jj] = pv; ps += pv; }
;       lsum[nt] += ps;
; #pragma unroll
;       for (int ks = 0; ks < 2; ++ks) {
;         u32x4 pk;
;         pk.x = cvt_pk_bf16(s[2 * ks][nt][0], s[2 * ks][nt][1]); pk.y = cvt_pk_bf16(s[2 * ks][nt][2], s[2 * ks][nt][3]);
;         pk.z = cvt_pk_bf16(s[2 * ks + 1][nt][0], s[2 * ks + 1][nt][1]); pk.w = cvt_pk_bf16(s[2 * ks + 1][nt][2], s[2 * ks + 1][nt][3]);
;         pf[nt][ks] = as_bf16x8(pk);
;       }
;     }
; #pragma unroll
;     for (int mt = 0; mt < 4; ++mt)
; #pragma unroll
;       for (int ks = 0; ks < 2; ++ks) {
;         const u32x2 lo = *(const u32x2*)(Vb + (16 * mt + lr) * 72 + 32 * ks + 4 * lq);
;         const u32x2 hi = *(const u32x2*)(Vb + (16 * mt + lr) * 72 + 32 * ks + 16 + 4 * lq);
;         const bf16x8 vf = as_bf16x8((u32x4){lo.x, lo.y, hi.x, hi.y});
;         oacc[mt][0] = MFMA16(vf, pf[0][ks], oacc[mt][0]);
;         oacc[mt][1] = MFMA16(vf, pf[1][ks], oacc[mt][1]);
;       }
;     stores(buf ^ 1, kregn, vregn);
;     __syncthreads();
.LBB0_869:
	v_sub_f32_e32 v98, v98, v202
	v_exp_f32_e32 v208, v98
	v_sub_f32_e32 v98, v99, v202
	v_exp_f32_e32 v209, v98
	v_sub_f32_e32 v98, v100, v202
	v_exp_f32_e32 v210, v98
	v_sub_f32_e32 v98, v101, v202
	v_exp_f32_e32 v211, v98
	v_sub_f32_e32 v98, v102, v202
	v_exp_f32_e32 v212, v98
	v_sub_f32_e32 v98, v103, v202
	v_sub_f32_e32 v114, v114, v203
	v_exp_f32_e32 v213, v98
	v_sub_f32_e32 v98, v104, v202
	v_exp_f32_e32 v227, v114
	v_sub_f32_e32 v114, v115, v203
	v_exp_f32_e32 v214, v98
	v_sub_f32_e32 v98, v105, v202
	v_exp_f32_e32 v228, v114
	v_sub_f32_e32 v114, v116, v203
	v_exp_f32_e32 v215, v98
	v_sub_f32_e32 v98, v110, v202
	v_exp_f32_e32 v229, v114
	v_sub_f32_e32 v114, v117, v203
	v_exp_f32_e32 v216, v98
	v_sub_f32_e32 v98, v111, v202
	v_exp_f32_e32 v230, v114
	v_sub_f32_e32 v114, v118, v203
	v_exp_f32_e32 v205, v98
	v_sub_f32_e32 v98, v112, v202
	v_exp_f32_e32 v231, v114
	v_sub_f32_e32 v114, v119, v203
	v_exp_f32_e32 v206, v98
	v_sub_f32_e32 v98, v113, v202
	v_add_u32_e32 v103, 0x6800, v184
	v_exp_f32_e32 v232, v114
	v_sub_f32_e32 v114, v120, v203
	v_exp_f32_e32 v207, v98
	ds_read2_b64 v[98:101], v103 offset1:4
	v_exp_f32_e32 v233, v114
	v_sub_f32_e32 v114, v121, v203
	v_exp_f32_e32 v234, v114
	v_sub_f32_e32 v114, v122, v203
	v_exp_f32_e32 v235, v114
	v_sub_f32_e32 v114, v123, v203
	v_exp_f32_e32 v204, v114
	v_sub_f32_e32 v114, v124, v203
	v_exp_f32_e32 v221, v114
	v_sub_f32_e32 v114, v125, v203
	v_sub_f32_e32 v102, v106, v202
	v_exp_f32_e32 v223, v114
	v_sub_f32_e32 v114, v126, v203
	v_exp_f32_e32 v219, v102
	v_sub_f32_e32 v102, v107, v202
	ds_read2_b64 v[110:113], v103 offset0:8 offset1:12
	v_exp_f32_e32 v225, v114
	v_sub_f32_e32 v114, v127, v203
	v_exp_f32_e32 v217, v102
	v_sub_f32_e32 v102, v108, v202
	v_exp_f32_e32 v222, v114
	v_sub_f32_e32 v114, v128, v203
	v_cvt_pk_bf16_f32 v118, v227, v228
	v_cvt_pk_bf16_f32 v119, v229, v230
	v_cvt_pk_bf16_f32 v120, v231, v232
	v_cvt_pk_bf16_f32 v121, v233, v234
	v_exp_f32_e32 v218, v102
	v_cvt_pk_bf16_f32 v102, v208, v209
	v_cvt_pk_bf16_f32 v103, v210, v211
	v_cvt_pk_bf16_f32 v104, v212, v213
	v_cvt_pk_bf16_f32 v105, v214, v215
	v_exp_f32_e32 v224, v114
	v_sub_f32_e32 v114, v129, v203
	s_waitcnt lgkmcnt(1)
	v_mfma_f32_16x16x32_bf16 v[94:97], v[98:101], v[118:121], v[94:97]
	v_exp_f32_e32 v226, v114
	v_cvt_pk_bf16_f32 v114, v235, v204
	v_cvt_pk_bf16_f32 v115, v221, v223
	v_mfma_f32_16x16x32_bf16 v[62:65], v[98:101], v[102:105], v[62:65]
	v_sub_f32_e32 v98, v109, v202
	v_exp_f32_e32 v220, v98
	v_cvt_pk_bf16_f32 v116, v225, v222
	v_cvt_pk_bf16_f32 v117, v224, v226
	v_cvt_pk_bf16_f32 v106, v216, v205
	v_cvt_pk_bf16_f32 v107, v206, v207
	v_cvt_pk_bf16_f32 v108, v219, v217
	v_cvt_pk_bf16_f32 v109, v218, v220
	v_add_u32_e32 v98, 0x7000, v184
	v_add_u32_e32 v254, 0x7800, v184
	v_add_u32_e32 v255, 0x8000, v184
	ds_read2_b64 v[242:245], v98 offset0:32 offset1:36
	ds_read2_b64 v[246:249], v98 offset0:40 offset1:44
	ds_read2_b64 v[250:253], v254 offset0:64 offset1:68
	s_waitcnt lgkmcnt(3)
	v_mfma_f32_16x16x32_bf16 v[130:133], v[110:113], v[114:117], v[94:97]
	s_min_i32 s6, s35, s37
	s_lshl_b32 s6, s6, 6
	s_ashr_i32 s7, s6, 31
	v_mfma_f32_16x16x32_bf16 v[94:97], v[110:113], v[106:109], v[62:65]
	s_lshl_b64 s[8:9], s[6:7], 1
	s_add_i32 s5, s5, 1
	s_cmp_lt_u32 s5, s34
	s_waitcnt lgkmcnt(2)
	v_mfma_f32_16x16x32_bf16 v[90:93], v[242:245], v[118:121], v[90:93]
	v_mfma_f32_16x16x32_bf16 v[46:49], v[242:245], v[102:105], v[46:49]
	ds_read2_b64 v[242:245], v254 offset0:72 offset1:76
	v_add_u32_e32 v98, 0x7800, v184
	s_waitcnt lgkmcnt(2)
	v_mfma_f32_16x16x32_bf16 v[134:137], v[246:249], v[114:117], v[90:93]
	v_mfma_f32_16x16x32_bf16 v[90:93], v[246:249], v[106:109], v[46:49]
	ds_read2_b64 v[246:249], v255 offset0:96 offset1:100
	s_nop 2
	s_waitcnt lgkmcnt(2)
	v_mfma_f32_16x16x32_bf16 v[62:65], v[250:253], v[118:121], v[74:77]
	v_mfma_f32_16x16x32_bf16 v[38:41], v[250:253], v[102:105], v[38:41]
	ds_read2_b64 v[250:253], v255 offset0:104 offset1:108
	s_waitcnt lgkmcnt(2)
	v_mfma_f32_16x16x32_bf16 v[138:141], v[242:245], v[114:117], v[62:65]
	s_nop 3
	v_add_u32_e32 v62, 0x8000, v184
	v_mfma_f32_16x16x32_bf16 v[98:101], v[242:245], v[106:109], v[38:41]
	s_nop 2
	s_waitcnt lgkmcnt(1)
	v_mfma_f32_16x16x32_bf16 v[46:49], v[246:249], v[118:121], v[66:69]
	v_mfma_f32_16x16x32_bf16 v[34:37], v[246:249], v[102:105], v[34:37]
	s_waitcnt vmcnt(9)
	ds_write_b128 v177, v[18:21] offset:13312
	s_waitcnt vmcnt(8)
	ds_write_b128 v178, v[26:29] offset:13312
	s_waitcnt vmcnt(7)
	ds_write_b128 v179, v[42:45] offset:13312
	s_waitcnt vmcnt(6)
	ds_write_b128 v180, v[70:73] offset:35840
	s_waitcnt vmcnt(5)
	ds_write_b128 v181, v[78:81] offset:35840
	s_waitcnt lgkmcnt(0)
	s_barrier
; #define MFMA16(a, b, c) __builtin_amdgcn_mfma_f32_16x16x32_bf16((a), (b), (c), 0, 0, 0)
; __device__ __forceinline__ void attn_unit(const WS& ws, int u, bool dry = false) {
;     ...
;   auto loadg = [&](int kt, u32x4 (&kreg)[3], u32x4 (&vreg)[2]) {
; #pragma unroll
;     for (int i = 0; i < 3; ++i) {
;       const int ci = tid + 256 * i; const int key = ci / 12, ch = ci - key * 12;
;       int gk = 64 * kt + key; if (gk > T_ - 1) gk = T_ - 1;
;       const bf16_t* src = ch < 8 ? ws.KN + (size_t)(b * T_ + gk) * 1024 + hd * 64 + ch * 8
;                                  : ws.KR + (size_t)(b * T_ + gk) * 32 + (ch - 8) * 8;
;       kreg[i] = *(const u32x4*)src;
;     }
; #pragma unroll
;     for (int i = 0; i < 2; ++i) {
;       const int ci = tid + 256 * i; const int dv = ci >> 3, ch = ci & 7;
;       vreg[i] = *(const u32x4*)(vbase + (size_t)dv * TP_ + 64 * kt + ch * 8);
;       if (64 * kt + ch * 8 >= T_) vreg[i] = (u32x4){0u, 0u, 0u, 0u};
;     }
;     ...
;   auto body = [&](int kt, int buf, u32x4 (&kreg)[3], u32x4 (&vreg)[2], const u32x4 (&kregn)[3], const u32x4 (&vregn)[2]) {
;     { const int kn = kt + 2 < nkt2 ? kt + 2 : nkt2 - 1; loadg(kn, kreg, vreg); }
;     const bf16_t* Kb = Kt + buf * 64 * 104;
;     const bf16_t* Vb = Vl + buf * 64 * 72;
;     f32x4 s[4][2];
; #pragma unroll
;     for (int mt = 0; mt < 4; ++mt) {
;       s[mt][0] = (f32x4){0.f, 0.f, 0.f, 0.f}; s[mt][1] = (f32x4){0.f, 0.f, 0.f, 0.f};
; #pragma unroll
;       for (int ks = 0; ks < 3; ++ks) {
;         const bf16x8 kf = *(const bf16x8*)(Kb + (16 * mt + lr) * 104 + 32 * ks + 8 * lq);
;         s[mt][0] = MFMA16(kf, xq[0][ks], s[mt][0]);
;         s[mt][1] = MFMA16(kf, xq[1][ks], s[mt][1]);
;       }
;     }
	ds_read_b128 v[242:245], v183 offset:13312
	ds_read_b128 v[246:249], v183 offset:13376
	v_mfma_f32_16x16x32_bf16 v[106:109], v[250:253], v[106:109], v[34:37]
	v_add_u32_e32 v42, s6, v171
	v_min_i32_e32 v42, 0x80f, v42
	s_waitcnt lgkmcnt(1)
	v_mfma_f32_16x16x32_bf16 v[34:37], v[242:245], v[0:3], 0
	v_mfma_f32_16x16x32_bf16 v[18:21], v[242:245], v[14:17], 0
	v_mfma_f32_16x16x32_bf16 v[142:145], v[250:253], v[114:117], v[46:49]
	ds_read_b128 v[250:253], v183 offset:13440
	ds_read_b128 v[242:245], v183 offset:16640
	s_waitcnt lgkmcnt(2)
	v_mfma_f32_16x16x32_bf16 v[34:37], v[246:249], v[4:7], v[34:37]
	s_nop 0
	v_add_u32_e32 v46, s66, v42
	v_ashrrev_i32_e32 v47, 31, v46
	v_lshlrev_b64 v[48:49], 11, v[46:47]
	v_mfma_f32_16x16x32_bf16 v[18:21], v[246:249], v[8:11], v[18:21]
	ds_read_b128 v[246:249], v183 offset:16704
	v_lshlrev_b64 v[46:47], 6, v[46:47]
	s_waitcnt lgkmcnt(2)
	v_mfma_f32_16x16x32_bf16 v[126:129], v[250:253], v[22:25], v[34:37]
	v_lshl_add_u64 v[62:63], v[154:155], 0, v[48:49]
	v_mfma_f32_16x16x32_bf16 v[34:37], v[250:253], v[30:33], v[18:21]
	ds_read_b128 v[250:253], v183 offset:16768
	s_nop 2
	s_waitcnt lgkmcnt(2)
	v_mfma_f32_16x16x32_bf16 v[26:29], v[242:245], v[0:3], 0
	v_mfma_f32_16x16x32_bf16 v[38:41], v[242:245], v[14:17], 0
	ds_read_b128 v[242:245], v183 offset:19968
	s_waitcnt lgkmcnt(2)
	v_mfma_f32_16x16x32_bf16 v[26:29], v[246:249], v[4:7], v[26:29]
	v_mfma_f32_16x16x32_bf16 v[38:41], v[246:249], v[8:11], v[38:41]
	ds_read_b128 v[246:249], v183 offset:20032
	v_lshl_add_u64 v[18:19], v[152:153], 0, v[46:47]
	v_lshl_add_u64 v[18:19], v[18:19], 0, s[86:87]
	s_waitcnt lgkmcnt(2)
	v_mfma_f32_16x16x32_bf16 v[122:125], v[250:253], v[22:25], v[26:29]
	v_cndmask_b32_e64 v18, v18, v62, s[38:39]
	v_cndmask_b32_e64 v19, v19, v63, s[38:39]
	global_load_dwordx4 v[18:21], v[18:19], off
	v_add_u32_e32 v26, s6, v172
	v_min_i32_e32 v62, 0x80f, v26
	v_add_u32_e32 v62, s66, v62
	v_ashrrev_i32_e32 v63, 31, v62
	v_lshlrev_b64 v[64:65], 11, v[62:63]
	v_lshl_add_u64 v[66:67], v[158:159], 0, v[64:65]
	v_lshlrev_b64 v[68:69], 6, v[62:63]
	v_mfma_f32_16x16x32_bf16 v[38:41], v[250:253], v[30:33], v[38:41]
	ds_read_b128 v[250:253], v183 offset:20096
	v_lshl_add_u64 v[68:69], v[156:157], 0, v[68:69]
	v_lshl_add_u64 v[68:69], v[68:69], 0, s[86:87]
	v_cndmask_b32_e64 v67, v69, v67, s[40:41]
	s_waitcnt lgkmcnt(2)
	v_mfma_f32_16x16x32_bf16 v[42:45], v[242:245], v[0:3], 0
	v_cndmask_b32_e64 v66, v68, v66, s[40:41]
	v_mfma_f32_16x16x32_bf16 v[46:49], v[242:245], v[14:17], 0
	ds_read_b128 v[242:245], v183 offset:23296
	s_waitcnt lgkmcnt(2)
	v_mfma_f32_16x16x32_bf16 v[42:45], v[246:249], v[4:7], v[42:45]
	v_mfma_f32_16x16x32_bf16 v[46:49], v[246:249], v[8:11], v[46:49]
	ds_read_b128 v[246:249], v183 offset:23360
	global_load_dwordx4 v[26:29], v[66:67], off
	s_waitcnt lgkmcnt(2)
	v_mfma_f32_16x16x32_bf16 v[118:121], v[250:253], v[22:25], v[42:45]
	v_mfma_f32_16x16x32_bf16 v[46:49], v[250:253], v[30:33], v[46:49]
	ds_read_b128 v[250:253], v183 offset:23424
	s_nop 0
	v_add_u32_e32 v42, s6, v173
	v_min_i32_e32 v42, 0x80f, v42
	v_add_u32_e32 v70, s66, v42
	s_waitcnt lgkmcnt(2)
	v_mfma_f32_16x16x32_bf16 v[42:45], v[242:245], v[0:3], 0
	v_ashrrev_i32_e32 v71, 31, v70
	v_lshlrev_b64 v[72:73], 11, v[70:71]
	v_lshlrev_b64 v[70:71], 6, v[70:71]
	v_lshl_add_u64 v[70:71], v[160:161], 0, v[70:71]
	v_mfma_f32_16x16x32_bf16 v[66:69], v[242:245], v[14:17], 0
	v_lshl_add_u64 v[78:79], v[162:163], 0, v[72:73]
	v_lshl_add_u64 v[80:81], v[70:71], 0, s[86:87]
	v_cndmask_b32_e64 v79, v81, v79, s[42:43]
	s_waitcnt lgkmcnt(1)
	v_mfma_f32_16x16x32_bf16 v[70:73], v[246:249], v[4:7], v[42:45]
	v_cndmask_b32_e64 v78, v80, v78, s[42:43]
	v_mfma_f32_16x16x32_bf16 v[62:65], v[246:249], v[8:11], v[66:69]
	s_nop 0
	global_load_dwordx4 v[42:45], v[78:79], off
	s_nop 0
	v_lshl_add_u64 v[66:67], v[148:149], 0, s[8:9]
	v_lshl_add_u64 v[68:69], v[150:151], 0, s[8:9]
	s_waitcnt lgkmcnt(0)
	v_mfma_f32_16x16x32_bf16 v[114:117], v[250:253], v[22:25], v[70:73]
	s_nop 2
	global_load_dwordx4 v[70:73], v[66:67], off
	global_load_dwordx4 v[78:81], v[68:69], off
	v_mfma_f32_16x16x32_bf16 v[62:65], v[250:253], v[30:33], v[62:65]
	s_cbranch_scc1 .LBB0_871
; __device__ __forceinline__ void attn_unit(const WS& ws, int u, bool dry = false) {
;     ...
;     if (kt >= 2 * qb) {
; #pragma unroll
;       for (int mt = 0; mt < 4; ++mt)
; #pragma unroll
;         for (int nt = 0; nt < 2; ++nt)
; #pragma unroll
;           for (int jj = 0; jj < 4; ++jj) {
;             const int key = 64 * kt + 16 * mt + 4 * lq + jj;
;             if (key > qi[nt]) s[mt][nt][jj] = -INFINITY;
;           }
;     }
	v_add_u32_e32 v67, 64, v185
	v_mov_b32_e32 v66, s17
	v_cmp_gt_i32_e32 vcc, v67, v169
	v_cmp_lt_i32_e64 s[44:45], v67, v169
	v_add_u32_e32 v68, 0x42, v185
	v_cndmask_b32_e32 v66, v126, v66, vcc
	v_cndmask_b32_e64 v126, v66, v126, s[44:45]
	v_cndmask_b32_e64 v127, v194, v127, s[44:45]
	v_cmp_le_i32_e64 s[44:45], v68, v169
	v_add_u32_e32 v69, 0x43, v185
	v_mov_b32_e32 v66, s17
	v_cndmask_b32_e64 v128, v194, v128, s[44:45]
	v_cmp_le_i32_e64 s[44:45], v69, v169
	v_add_u32_e32 v74, 0x63, v185
	s_nop 0
	v_cndmask_b32_e64 v129, v194, v129, s[44:45]
	v_cmp_gt_i32_e64 s[44:45], v67, v13
	s_nop 1
	v_cndmask_b32_e64 v66, v34, v66, s[44:45]
	v_cmp_lt_i32_e64 s[44:45], v67, v13
	v_add_u32_e32 v67, 0x50, v185
	s_nop 0
	v_cndmask_b32_e64 v34, v66, v34, s[44:45]
	v_cndmask_b32_e64 v35, v194, v35, s[44:45]
	v_cmp_le_i32_e64 s[44:45], v68, v13
	v_mov_b32_e32 v66, s17
	v_add_u32_e32 v68, 0x52, v185
	v_cndmask_b32_e64 v36, v194, v36, s[44:45]
	v_cmp_le_i32_e64 s[44:45], v69, v13
	v_cndmask_b32_e32 v38, v38, v66, vcc
	v_add_u32_e32 v69, 0x53, v185
	v_cndmask_b32_e64 v37, v194, v37, s[44:45]
	v_cmp_gt_i32_e64 s[44:45], v67, v169
	v_add_u32_e32 v67, 0x51, v185
	v_cmp_le_i32_e32 vcc, v67, v13
	v_cndmask_b32_e64 v122, v122, v66, s[44:45]
	v_cmp_le_i32_e64 s[44:45], v67, v169
	v_cndmask_b32_e32 v39, v194, v39, vcc
	v_cmp_le_i32_e32 vcc, v68, v13
	v_add_u32_e32 v67, 0x60, v185
	v_cndmask_b32_e64 v123, v194, v123, s[44:45]
	v_cndmask_b32_e32 v40, v194, v40, vcc
	v_cmp_le_i32_e32 vcc, v69, v13
	v_cmp_le_i32_e64 s[44:45], v68, v169
	v_add_u32_e32 v68, 0x61, v185
	v_cndmask_b32_e32 v41, v194, v41, vcc
	v_cmp_gt_i32_e32 vcc, v67, v169
	v_cndmask_b32_e64 v124, v194, v124, s[44:45]
	v_cmp_le_i32_e64 s[44:45], v69, v169
	v_cndmask_b32_e32 v118, v118, v66, vcc
	v_cmp_le_i32_e32 vcc, v68, v169
	v_add_u32_e32 v69, 0x62, v185
	v_cndmask_b32_e64 v125, v194, v125, s[44:45]
	v_cndmask_b32_e32 v119, v194, v119, vcc
	v_cmp_le_i32_e32 vcc, v69, v169
	s_nop 1
	v_cndmask_b32_e32 v120, v194, v120, vcc
	v_cmp_le_i32_e32 vcc, v74, v169
	s_nop 1
	v_cndmask_b32_e32 v121, v194, v121, vcc
	v_cmp_gt_i32_e32 vcc, v67, v13
	v_add_u32_e32 v67, 0x70, v185
	s_nop 0
	v_cndmask_b32_e32 v46, v46, v66, vcc
	v_cmp_le_i32_e32 vcc, v68, v13
	v_add_u32_e32 v68, 0x71, v185
	s_nop 0
	v_cndmask_b32_e32 v47, v194, v47, vcc
	v_cmp_le_i32_e32 vcc, v69, v13
	v_add_u32_e32 v69, 0x72, v185
	s_nop 0
	v_cndmask_b32_e32 v48, v194, v48, vcc
	v_cmp_le_i32_e32 vcc, v74, v13
	v_add_u32_e32 v74, 0x73, v185
	s_nop 0
	v_cndmask_b32_e32 v49, v194, v49, vcc
	v_cmp_gt_i32_e32 vcc, v67, v169
	s_nop 1
	v_cndmask_b32_e32 v114, v114, v66, vcc
	v_cmp_le_i32_e32 vcc, v68, v169
	s_nop 1
	v_cndmask_b32_e32 v115, v194, v115, vcc
	v_cmp_le_i32_e32 vcc, v69, v169
	s_nop 1
	v_cndmask_b32_e32 v116, v194, v116, vcc
	v_cmp_le_i32_e32 vcc, v74, v169
	s_nop 1
	v_cndmask_b32_e32 v117, v194, v117, vcc
	v_cmp_gt_i32_e32 vcc, v67, v13
	s_nop 1
	v_cndmask_b32_e32 v62, v62, v66, vcc
	v_cmp_le_i32_e32 vcc, v68, v13
	s_nop 1
	v_cndmask_b32_e32 v63, v194, v63, vcc
	v_cmp_le_i32_e32 vcc, v69, v13
	s_nop 1
	v_cndmask_b32_e32 v64, v194, v64, vcc
	v_cmp_le_i32_e32 vcc, v74, v13
	s_nop 1
	v_cndmask_b32_e32 v65, v194, v65, vcc
